# adds nt on P2 read-once loads (raw qkv rows of both groups, sample K/V caches)
# baseline (speedup 1.0000x reference)
; __device__ __forceinline__ void gdn_prep_all(const Params& P, LAS unsigned char* lds, int tid, int lane, int wave, int G) {
;     ...
;     if ((int)blockIdx.x < NCU * 4) { GDN_PREFETCH((int)blockIdx.x); if (wq == 0) GDN_GATES(scb0, (int)blockIdx.x); }
.LBB0_322:
	s_or_b64 exec, exec, s[10:11]
	s_cmp_eq_u32 s5, 0
	s_cselect_b64 s[10:11], -1, 0
	v_readlane_b32 s12, v247, 47
	s_or_b64 s[10:11], s[8:9], s[10:11]
	v_add_u32_e32 v2, s15, v100
	v_readlane_b32 s13, v247, 48
	v_lshl_or_b32 v6, v2, 6, v79
	s_and_b64 s[10:11], s[10:11], s[12:13]
	s_xor_b64 s[10:11], s[10:11], -1
	v_ashrrev_i32_e32 v7, 31, v6
	s_ashr_i32 s5, s4, 31
	s_and_saveexec_b64 s[12:13], s[10:11]
	s_xor_b64 s[10:11], exec, s[12:13]
	s_cbranch_execz .LBB0_324
	v_lshl_add_u64 v[2:3], v[6:7], 1, s[66:67]
	v_lshl_add_u64 v[4:5], s[4:5], 0, v[82:83]
	s_movk_i32 s18, 0xc00
	v_mad_u64_u32 v[2:3], s[12:13], v4, s18, v[2:3]
	v_mad_i32_i24 v3, v5, s18, v3
	global_load_dwordx4 v[2:5], v[2:3], off nt

.LBB0_328:
	s_or_b64 exec, exec, s[10:11]
	v_mov_b32_e32 v10, 0
	v_mov_b32_e32 v11, v10
	v_mov_b32_e32 v12, v10
	v_mov_b32_e32 v13, v10
	v_mov_b64_e32 v[6:7], v[10:11]
	v_cmp_gt_u32_e32 vcc, s24, v84
	v_mov_b64_e32 v[8:9], v[12:13]
	s_and_saveexec_b64 s[8:9], vcc
	s_cbranch_execz .LBB0_330
	v_add_u32_e32 v6, s15, v101
	v_lshl_or_b32 v6, v6, 6, v79
	v_ashrrev_i32_e32 v7, 31, v6
	v_lshl_add_u64 v[6:7], v[6:7], 1, s[66:67]
	v_lshl_add_u64 v[8:9], s[4:5], 0, v[84:85]
	s_movk_i32 s12, 0xc00
	v_mad_u64_u32 v[6:7], s[10:11], v8, s12, v[6:7]
	v_mad_i32_i24 v7, v9, s12, v7
	global_load_dwordx4 v[6:9], v[6:7], off nt
.LBB0_330:
	s_or_b64 exec, exec, s[8:9]
	v_cmp_gt_u32_e32 vcc, s24, v86
	s_and_saveexec_b64 s[8:9], vcc
	s_cbranch_execz .LBB0_332
	v_add_u32_e32 v10, s15, v102
	v_lshl_or_b32 v10, v10, 6, v79
	v_ashrrev_i32_e32 v11, 31, v10
	v_lshl_add_u64 v[10:11], v[10:11], 1, s[66:67]
	v_lshl_add_u64 v[12:13], s[4:5], 0, v[86:87]
	s_movk_i32 s12, 0xc00
	v_mad_u64_u32 v[10:11], s[10:11], v12, s12, v[10:11]
	v_mad_i32_i24 v11, v13, s12, v11
	global_load_dwordx4 v[10:13], v[10:11], off nt
.LBB0_332:
	s_or_b64 exec, exec, s[8:9]
	v_mov_b32_e32 v18, 0
	v_mov_b32_e32 v19, v18
	v_mov_b32_e32 v20, v18
	v_mov_b32_e32 v21, v18
	v_mov_b64_e32 v[14:15], v[18:19]
	v_cmp_gt_u32_e32 vcc, s24, v88
	v_mov_b64_e32 v[16:17], v[20:21]
	s_and_saveexec_b64 s[8:9], vcc
	s_cbranch_execz .LBB0_334
	v_add_u32_e32 v14, s15, v103
	v_lshl_or_b32 v14, v14, 6, v79
	v_ashrrev_i32_e32 v15, 31, v14
	v_lshl_add_u64 v[14:15], v[14:15], 1, s[66:67]
	v_lshl_add_u64 v[16:17], s[4:5], 0, v[88:89]
	s_movk_i32 s12, 0xc00
	v_mad_u64_u32 v[14:15], s[10:11], v16, s12, v[14:15]
	v_mad_i32_i24 v15, v17, s12, v15
	global_load_dwordx4 v[14:17], v[14:15], off nt
.LBB0_334:
	s_or_b64 exec, exec, s[8:9]
	v_cmp_gt_u32_e32 vcc, s24, v90
	s_and_saveexec_b64 s[8:9], vcc
	s_cbranch_execz .LBB0_336
	v_add_u32_e32 v18, s15, v104
	v_lshl_or_b32 v18, v18, 6, v79
	v_ashrrev_i32_e32 v19, 31, v18
	v_lshl_add_u64 v[18:19], v[18:19], 1, s[66:67]
	v_lshl_add_u64 v[20:21], s[4:5], 0, v[90:91]
	s_movk_i32 s12, 0xc00
	v_mad_u64_u32 v[18:19], s[10:11], v20, s12, v[18:19]
	v_mad_i32_i24 v19, v21, s12, v19
	global_load_dwordx4 v[18:21], v[18:19], off nt
.LBB0_336:
	s_or_b64 exec, exec, s[8:9]
	v_mov_b32_e32 v26, 0
	v_mov_b32_e32 v27, v26
	v_mov_b32_e32 v28, v26
	v_mov_b32_e32 v29, v26
	v_mov_b64_e32 v[22:23], v[26:27]
	v_cmp_gt_u32_e32 vcc, s24, v92
	v_mov_b64_e32 v[24:25], v[28:29]
	s_and_saveexec_b64 s[8:9], vcc
	s_cbranch_execz .LBB0_338
	v_add_u32_e32 v22, s15, v105
	v_lshl_or_b32 v22, v22, 6, v79
	v_ashrrev_i32_e32 v23, 31, v22
	v_lshl_add_u64 v[22:23], v[22:23], 1, s[66:67]
	v_lshl_add_u64 v[24:25], s[4:5], 0, v[92:93]
	s_movk_i32 s12, 0xc00
	v_mad_u64_u32 v[22:23], s[10:11], v24, s12, v[22:23]
	v_mad_i32_i24 v23, v25, s12, v23
	global_load_dwordx4 v[22:25], v[22:23], off nt
.LBB0_338:
	s_or_b64 exec, exec, s[8:9]
	v_cmp_gt_u32_e32 vcc, s24, v94
	s_and_b64 s[10:11], s[34:35], vcc
	s_and_saveexec_b64 s[8:9], s[10:11]
	s_cbranch_execz .LBB0_340
	v_add_u32_e32 v26, s15, v106
	v_lshl_or_b32 v26, v26, 6, v79
	v_ashrrev_i32_e32 v27, 31, v26
	v_lshl_add_u64 v[26:27], v[26:27], 1, s[66:67]
	v_lshl_add_u64 v[28:29], s[4:5], 0, v[94:95]
	s_movk_i32 s10, 0xc00
	v_mad_u64_u32 v[26:27], s[4:5], v28, s10, v[26:27]
	v_mad_i32_i24 v27, v29, s10, v27
	global_load_dwordx4 v[26:29], v[26:27], off nt

; __device__ __forceinline__ void gdn_prep_all(const Params& P, LAS unsigned char* lds, int tid, int lane, int wave, int G) {
;     ...
;         if (item + G < NCU * 4) GDN_PREFETCH(item + G);
.LBB0_362:
	s_ashr_i32 s57, s56, 31
	s_cmp_eq_u32 s61, 0
	s_cselect_b64 s[12:13], -1, 0
	v_readlane_b32 s14, v247, 47
	s_or_b64 s[12:13], s[58:59], s[12:13]
	v_readlane_b32 s15, v247, 48
	v_add_u32_e32 v2, s51, v100
	s_and_b64 s[12:13], s[14:15], s[12:13]
	v_lshl_or_b32 v6, v2, 6, v79
	s_xor_b64 s[12:13], s[12:13], -1
	s_and_saveexec_b64 s[14:15], s[12:13]
	s_xor_b64 s[14:15], exec, s[14:15]
	s_cbranch_execz .LBB0_364
	v_lshl_add_u64 v[2:3], s[56:57], 0, v[82:83]
	v_mov_b64_e32 v[4:5], s[66:67]
	v_mad_u64_u32 v[4:5], s[12:13], v2, s97, v[4:5]
	v_mad_i32_i24 v5, v3, s97, v5
	v_ashrrev_i32_e32 v7, 31, v6
	v_lshl_add_u64 v[2:3], v[6:7], 1, v[4:5]
	global_load_dwordx4 v[2:5], v[2:3], off nt

; __device__ __forceinline__ void gdn_prep_all(const Params& P, LAS unsigned char* lds, int tid, int lane, int wave, int G) {
;     ...
;         if (item + G < NCU * 4) GDN_PREFETCH(item + G);
.LBB0_368:
	s_or_b64 exec, exec, s[14:15]
	v_mov_b32_e32 v31, v30
	v_mov_b32_e32 v32, v30
	v_mov_b32_e32 v33, v30
	v_mov_b64_e32 v[6:7], v[30:31]
	v_cmp_gt_u32_e32 vcc, s50, v84
	v_mov_b64_e32 v[8:9], v[32:33]
	s_and_saveexec_b64 s[14:15], vcc
	s_cbranch_execz .LBB0_370
	v_add_u32_e32 v6, s51, v101
	v_lshl_add_u64 v[8:9], s[56:57], 0, v[84:85]
	v_mov_b64_e32 v[10:11], s[66:67]
	v_lshl_or_b32 v6, v6, 6, v79
	v_mad_u64_u32 v[10:11], s[12:13], v8, s97, v[10:11]
	v_mad_i32_i24 v11, v9, s97, v11
	v_ashrrev_i32_e32 v7, 31, v6
	v_lshl_add_u64 v[6:7], v[6:7], 1, v[10:11]
	global_load_dwordx4 v[6:9], v[6:7], off nt
.LBB0_370:
	s_or_b64 exec, exec, s[14:15]
	v_mov_b64_e32 v[10:11], v[30:31]
	v_cmp_gt_u32_e32 vcc, s50, v86
	v_mov_b64_e32 v[12:13], v[32:33]
	s_and_saveexec_b64 s[14:15], vcc
	s_cbranch_execz .LBB0_372
	v_add_u32_e32 v10, s51, v102
	v_lshl_add_u64 v[12:13], s[56:57], 0, v[86:87]
	v_mov_b64_e32 v[14:15], s[66:67]
	v_lshl_or_b32 v10, v10, 6, v79
	v_mad_u64_u32 v[14:15], s[12:13], v12, s97, v[14:15]
	v_mad_i32_i24 v15, v13, s97, v15
	v_ashrrev_i32_e32 v11, 31, v10
	v_lshl_add_u64 v[10:11], v[10:11], 1, v[14:15]
	global_load_dwordx4 v[10:13], v[10:11], off nt
.LBB0_372:
	s_or_b64 exec, exec, s[14:15]
	v_mov_b32_e32 v31, v30
	v_mov_b32_e32 v32, v30
	v_mov_b32_e32 v33, v30
	v_mov_b64_e32 v[14:15], v[30:31]
	v_cmp_gt_u32_e32 vcc, s50, v88
	v_mov_b64_e32 v[16:17], v[32:33]
	s_and_saveexec_b64 s[14:15], vcc
	s_cbranch_execz .LBB0_374
	v_add_u32_e32 v14, s51, v103
	v_lshl_add_u64 v[16:17], s[56:57], 0, v[88:89]
	v_mov_b64_e32 v[18:19], s[66:67]
	v_lshl_or_b32 v14, v14, 6, v79
	v_mad_u64_u32 v[18:19], s[12:13], v16, s97, v[18:19]
	v_mad_i32_i24 v19, v17, s97, v19
	v_ashrrev_i32_e32 v15, 31, v14
	v_lshl_add_u64 v[14:15], v[14:15], 1, v[18:19]
	global_load_dwordx4 v[14:17], v[14:15], off nt
.LBB0_374:
	s_or_b64 exec, exec, s[14:15]
	v_mov_b64_e32 v[18:19], v[30:31]
	v_cmp_gt_u32_e32 vcc, s50, v90
	v_mov_b64_e32 v[20:21], v[32:33]
	s_and_saveexec_b64 s[14:15], vcc
	s_cbranch_execz .LBB0_376
	v_add_u32_e32 v18, s51, v104
	v_lshl_add_u64 v[20:21], s[56:57], 0, v[90:91]
	v_mov_b64_e32 v[22:23], s[66:67]
	v_lshl_or_b32 v18, v18, 6, v79
	v_mad_u64_u32 v[22:23], s[12:13], v20, s97, v[22:23]
	v_mad_i32_i24 v23, v21, s97, v23
	v_ashrrev_i32_e32 v19, 31, v18
	v_lshl_add_u64 v[18:19], v[18:19], 1, v[22:23]
	global_load_dwordx4 v[18:21], v[18:19], off nt
.LBB0_376:
	s_or_b64 exec, exec, s[14:15]
	v_mov_b32_e32 v31, v30
	v_mov_b32_e32 v32, v30
	v_mov_b32_e32 v33, v30
	v_mov_b64_e32 v[22:23], v[30:31]
	v_cmp_gt_u32_e32 vcc, s50, v92
	v_mov_b64_e32 v[24:25], v[32:33]
	s_and_saveexec_b64 s[14:15], vcc
	s_cbranch_execz .LBB0_378
	v_add_u32_e32 v22, s51, v105
	v_lshl_add_u64 v[24:25], s[56:57], 0, v[92:93]
	v_mov_b64_e32 v[26:27], s[66:67]
	v_lshl_or_b32 v22, v22, 6, v79
	v_mad_u64_u32 v[26:27], s[12:13], v24, s97, v[26:27]
	v_mad_i32_i24 v27, v25, s97, v27
	v_ashrrev_i32_e32 v23, 31, v22
	v_lshl_add_u64 v[22:23], v[22:23], 1, v[26:27]
	global_load_dwordx4 v[22:25], v[22:23], off nt
.LBB0_378:
	s_or_b64 exec, exec, s[14:15]
	v_cmp_gt_u32_e32 vcc, s50, v94
	v_mov_b64_e32 v[26:27], v[30:31]
	s_and_b64 s[12:13], s[34:35], vcc
	v_mov_b64_e32 v[28:29], v[32:33]
	s_and_saveexec_b64 s[14:15], s[12:13]
	s_cbranch_execz .LBB0_380
	v_add_u32_e32 v26, s51, v106
	v_lshl_add_u64 v[28:29], s[56:57], 0, v[94:95]
	v_mov_b64_e32 v[32:33], s[66:67]
	v_lshl_or_b32 v26, v26, 6, v79
	v_mad_u64_u32 v[32:33], s[12:13], v28, s97, v[32:33]
	v_mad_i32_i24 v33, v29, s97, v33
	v_ashrrev_i32_e32 v27, 31, v26
	v_lshl_add_u64 v[26:27], v[26:27], 1, v[32:33]
	global_load_dwordx4 v[26:29], v[26:27], off nt

; __device__ __forceinline__ void bprep_item(const Params& P, LAS unsigned char* lds, int item, int tid, int lane, int wave) {
;     ...
;         for (int hi = 0; hi < 4; ++hi) { const int h = hb4 + hi;
;             if (mode != 2) { wq_[hi] = wk_[hi] = wv_[hi] = (v4u){0u, 0u, 0u, 0u};
;                 if (valid) { const bf16* rp = QKVB + (size_t)m * 1536 + h * 64 + 8 * part; wq_[hi] = *(const v4u*)rp; wk_[hi] = *(const v4u*)(rp + 512); wv_[hi] = *(const v4u*)(rp + 1024); } }
;             else { const size_t co = (((size_t)s * 512 + 64 * pi + tl) * 8 + h) * 64 + 8 * part;
;                 ck_[hi][0] = ((const f32x4*)(P.cache_k + co))[0]; ck_[hi][1] = ((const f32x4*)(P.cache_k + co))[1]; cv_[hi][0] = ((const f32x4*)(P.cache_v + co))[0]; cv_[hi][1] = ((const f32x4*)(P.cache_v + co))[1]; } }
.LBB0_495:
	global_load_dwordx4 v[42:45], v[152:153], off offset:16 nt
	global_load_dwordx4 v[46:49], v[152:153], off nt
	global_load_dwordx4 v[50:53], v[154:155], off offset:16 nt
	global_load_dwordx4 v[54:57], v[154:155], off nt
	v_mad_u64_u32 v[174:175], s[18:19], v2, s51, v[156:157]
	v_mov_b32_e32 v2, v175
	v_mad_u64_u32 v[2:3], s[18:19], v3, s51, v[2:3]
	s_lshl_b32 s8, s61, 6
	v_mov_b32_e32 v175, v2
	v_lshl_add_u64 v[2:3], s[8:9], 0, v[138:139]
	s_lshl_b64 s[18:19], s[38:39], 18
	v_lshlrev_b64 v[2:3], 9, v[2:3]
	v_lshl_add_u64 v[176:177], s[18:19], 0, v[2:3]
	v_lshlrev_b64 v[2:3], 15, v[4:5]
	v_lshl_add_u64 v[2:3], s[48:49], 0, v[2:3]
	v_lshl_add_u64 v[178:179], v[2:3], 0, v[146:147]
	v_lshlrev_b64 v[2:3], 15, v[6:7]
	v_lshl_add_u64 v[2:3], s[46:47], 0, v[2:3]
	s_lshl_b64 s[18:19], s[38:39], 7
	v_add_u32_e32 v6, s62, v138
	v_lshl_add_u64 v[180:181], v[2:3], 0, v[146:147]
	v_lshl_add_u64 v[2:3], s[18:19], 0, v[160:161]
	v_add_u32_e32 v150, 0xffffe200, v6
	s_lshl_b64 s[18:19], s[38:39], 12
	v_lshl_add_u64 v[4:5], v[150:151], 3, s[18:19]
	s_and_b64 s[6:7], s[0:1], s[6:7]
	v_cmp_lt_i32_e32 vcc, s60, v6
	v_cndmask_b32_e64 v1, v3, v5, s[4:5]
	v_cndmask_b32_e64 v150, v2, v4, s[4:5]
	v_cndmask_b32_e64 v2, 0, 1, s[6:7]
	v_cndmask_b32_e64 v3, 0, 1, vcc
	v_cndmask_b32_e64 v2, v2, v3, s[4:5]
	v_and_b32_e32 v2, 1, v2
	s_xor_b64 s[40:41], s[40:41], -1
	s_mov_b64 s[44:45], -1
	s_or_b64 s[42:43], s[0:1], s[36:37]
	v_or_b32_e32 v176, v176, v148
	v_cndmask_b32_e64 v183, v163, v165, s[4:5]
	v_cndmask_b32_e64 v182, v162, v164, s[4:5]
	v_cmp_eq_u32_e64 s[6:7], 1, v2
	v_cndmask_b32_e64 v185, v167, v169, s[4:5]
	v_cndmask_b32_e64 v184, v166, v168, s[4:5]
	s_mov_b32 s8, 0
	s_branch .LBB0_497

; __device__ __forceinline__ void bprep_item(const Params& P, LAS unsigned char* lds, int item, int tid, int lane, int wave) {
;     ...
;         for (int hi = 0; hi < 4; ++hi) { const int h = hb4 + hi;
;             if (mode != 2) { wq_[hi] = wk_[hi] = wv_[hi] = (v4u){0u, 0u, 0u, 0u};
;                 if (valid) { const bf16* rp = QKVB + (size_t)m * 1536 + h * 64 + 8 * part; wq_[hi] = *(const v4u*)rp; wk_[hi] = *(const v4u*)(rp + 512); wv_[hi] = *(const v4u*)(rp + 1024); } }
.LBB0_497:
	v_cndmask_b32_e64 v90, 0, 1, s[40:41]
	v_cmp_ne_u32_e64 s[4:5], 1, v90
	s_andn2_b64 vcc, exec, s[40:41]
	s_mov_b64 s[46:47], -1
	s_cbranch_vccnz .LBB0_501
	v_mov_b32_e32 v93, 0
	v_mov_b32_e32 v92, 0
	v_mov_b32_e32 v91, 0
	v_mov_b32_e32 v90, 0
	v_mov_b32_e32 v97, 0
	v_mov_b32_e32 v96, 0
	v_mov_b32_e32 v95, 0
	v_mov_b32_e32 v94, 0
	v_mov_b32_e32 v101, 0
	v_mov_b32_e32 v100, 0
	v_mov_b32_e32 v99, 0
	v_mov_b32_e32 v98, 0
	s_and_saveexec_b64 s[46:47], s[42:43]
	s_cbranch_execz .LBB0_500
	s_lshl_b32 s18, s8, 7
	s_mov_b32 s19, s9
	v_lshl_add_u64 v[90:91], v[174:175], 0, s[18:19]
	global_load_dwordx4 v[98:101], v[90:91], off nt
	global_load_dwordx4 v[94:97], v[90:91], off offset:1024 nt
	s_nop 0
	global_load_dwordx4 v[90:93], v[90:91], off offset:2048 nt

; __device__ __forceinline__ void bprep_item(const Params& P, LAS unsigned char* lds, int item, int tid, int lane, int wave) {
;     ...
;         for (int hi = 0; hi < 4; ++hi) { const int h = hb4 + hi;
;             if (mode != 2) { wq_[hi] = wk_[hi] = wv_[hi] = (v4u){0u, 0u, 0u, 0u};
;                 if (valid) { const bf16* rp = QKVB + (size_t)m * 1536 + h * 64 + 8 * part; wq_[hi] = *(const v4u*)rp; wk_[hi] = *(const v4u*)(rp + 512); wv_[hi] = *(const v4u*)(rp + 1024); } }
;             else { const size_t co = (((size_t)s * 512 + 64 * pi + tl) * 8 + h) * 64 + 8 * part;
;                 ck_[hi][0] = ((const f32x4*)(P.cache_k + co))[0]; ck_[hi][1] = ((const f32x4*)(P.cache_k + co))[1]; cv_[hi][0] = ((const f32x4*)(P.cache_v + co))[0]; cv_[hi][1] = ((const f32x4*)(P.cache_v + co))[1]; } }
.LBB0_502:
	v_lshl_or_b32 v26, s8, 6, v176
	v_mov_b32_e32 v27, v177
	v_lshlrev_b64 v[26:27], 2, v[26:27]
	v_lshl_add_u64 v[28:29], s[76:77], 0, v[26:27]
	v_lshl_add_u64 v[26:27], s[78:79], 0, v[26:27]
	global_load_dwordx4 v[82:85], v[28:29], off offset:16 nt
	global_load_dwordx4 v[86:89], v[28:29], off nt
	global_load_dwordx4 v[30:33], v[26:27], off offset:16 nt
	s_nop 0
	global_load_dwordx4 v[26:29], v[26:27], off nt
	s_waitcnt vmcnt(6)
	v_mov_b32_e32 v98, v110
	v_mov_b32_e32 v99, v111
	v_mov_b32_e32 v100, v112
	v_mov_b32_e32 v101, v113
	s_waitcnt vmcnt(5)
	v_mov_b32_e32 v94, v106
	v_mov_b32_e32 v95, v107
	v_mov_b32_e32 v96, v108
	v_mov_b32_e32 v97, v109
	s_waitcnt vmcnt(4)
	v_mov_b32_e32 v90, v102
	v_mov_b32_e32 v91, v103
	v_mov_b32_e32 v92, v104
	v_mov_b32_e32 v93, v105
.LBB0_503:
	s_or_b32 s52, s8, 1
	s_and_b64 vcc, exec, s[4:5]
	s_mov_b64 s[46:47], -1
	s_cbranch_vccnz .LBB0_507
	v_mov_b32_e32 v105, 0
	v_mov_b32_e32 v104, 0
	v_mov_b32_e32 v103, 0
	v_mov_b32_e32 v102, 0
	v_mov_b32_e32 v109, 0
	v_mov_b32_e32 v108, 0
	v_mov_b32_e32 v107, 0
	v_mov_b32_e32 v106, 0
	v_mov_b32_e32 v113, 0
	v_mov_b32_e32 v112, 0
	v_mov_b32_e32 v111, 0
	v_mov_b32_e32 v110, 0
	s_and_saveexec_b64 s[46:47], s[42:43]
	s_cbranch_execz .LBB0_506
	s_lshl_b32 s18, s52, 7
	s_mov_b32 s19, s9
	v_lshl_add_u64 v[102:103], v[174:175], 0, s[18:19]
	global_load_dwordx4 v[110:113], v[102:103], off nt
	global_load_dwordx4 v[106:109], v[102:103], off offset:1024 nt
	s_nop 0
	global_load_dwordx4 v[102:105], v[102:103], off offset:2048 nt

; __device__ __forceinline__ void bprep_item(const Params& P, LAS unsigned char* lds, int item, int tid, int lane, int wave) {
;     ...
;         for (int hi = 0; hi < 4; ++hi) { const int h = hb4 + hi;
;             if (mode != 2) { wq_[hi] = wk_[hi] = wv_[hi] = (v4u){0u, 0u, 0u, 0u};
;                 if (valid) { const bf16* rp = QKVB + (size_t)m * 1536 + h * 64 + 8 * part; wq_[hi] = *(const v4u*)rp; wk_[hi] = *(const v4u*)(rp + 512); wv_[hi] = *(const v4u*)(rp + 1024); } }
;             else { const size_t co = (((size_t)s * 512 + 64 * pi + tl) * 8 + h) * 64 + 8 * part;
;                 ck_[hi][0] = ((const f32x4*)(P.cache_k + co))[0]; ck_[hi][1] = ((const f32x4*)(P.cache_k + co))[1]; cv_[hi][0] = ((const f32x4*)(P.cache_v + co))[0]; cv_[hi][1] = ((const f32x4*)(P.cache_v + co))[1]; } }
.LBB0_508:
	v_lshl_or_b32 v18, s52, 6, v176
	v_mov_b32_e32 v19, v177
	v_lshlrev_b64 v[18:19], 2, v[18:19]
	v_lshl_add_u64 v[20:21], s[76:77], 0, v[18:19]
	v_lshl_add_u64 v[18:19], s[78:79], 0, v[18:19]
	global_load_dwordx4 v[74:77], v[20:21], off offset:16 nt
	global_load_dwordx4 v[78:81], v[20:21], off nt
	global_load_dwordx4 v[22:25], v[18:19], off offset:16 nt
	s_nop 0
	global_load_dwordx4 v[18:21], v[18:19], off nt
	s_waitcnt vmcnt(6)
	v_mov_b32_e32 v110, v122
	v_mov_b32_e32 v111, v123
	v_mov_b32_e32 v112, v124
	v_mov_b32_e32 v113, v125
	s_waitcnt vmcnt(5)
	v_mov_b32_e32 v106, v118
	v_mov_b32_e32 v107, v119
	v_mov_b32_e32 v108, v120
	v_mov_b32_e32 v109, v121
	s_waitcnt vmcnt(4)
	v_mov_b32_e32 v102, v114
	v_mov_b32_e32 v103, v115
	v_mov_b32_e32 v104, v116
	v_mov_b32_e32 v105, v117
.LBB0_509:
	s_or_b32 s48, s8, 2
	s_and_b64 vcc, exec, s[4:5]
	s_mov_b64 s[46:47], -1
	s_cbranch_vccnz .LBB0_513
	v_mov_b32_e32 v117, 0
	v_mov_b32_e32 v116, 0
	v_mov_b32_e32 v115, 0
	v_mov_b32_e32 v114, 0
	v_mov_b32_e32 v121, 0
	v_mov_b32_e32 v120, 0
	v_mov_b32_e32 v119, 0
	v_mov_b32_e32 v118, 0
	v_mov_b32_e32 v125, 0
	v_mov_b32_e32 v124, 0
	v_mov_b32_e32 v123, 0
	v_mov_b32_e32 v122, 0
	s_and_saveexec_b64 s[46:47], s[42:43]
	s_cbranch_execz .LBB0_512
	s_lshl_b32 s18, s48, 7
	s_mov_b32 s19, s9
	v_lshl_add_u64 v[114:115], v[174:175], 0, s[18:19]
	global_load_dwordx4 v[122:125], v[114:115], off nt
	global_load_dwordx4 v[118:121], v[114:115], off offset:1024 nt
	s_nop 0
	global_load_dwordx4 v[114:117], v[114:115], off offset:2048 nt

; __device__ __forceinline__ void bprep_item(const Params& P, LAS unsigned char* lds, int item, int tid, int lane, int wave) {
;     ...
;         for (int hi = 0; hi < 4; ++hi) { const int h = hb4 + hi;
;             if (mode != 2) { wq_[hi] = wk_[hi] = wv_[hi] = (v4u){0u, 0u, 0u, 0u};
;                 if (valid) { const bf16* rp = QKVB + (size_t)m * 1536 + h * 64 + 8 * part; wq_[hi] = *(const v4u*)rp; wk_[hi] = *(const v4u*)(rp + 512); wv_[hi] = *(const v4u*)(rp + 1024); } }
;             else { const size_t co = (((size_t)s * 512 + 64 * pi + tl) * 8 + h) * 64 + 8 * part;
;                 ck_[hi][0] = ((const f32x4*)(P.cache_k + co))[0]; ck_[hi][1] = ((const f32x4*)(P.cache_k + co))[1]; cv_[hi][0] = ((const f32x4*)(P.cache_v + co))[0]; cv_[hi][1] = ((const f32x4*)(P.cache_v + co))[1]; } }
.LBB0_514:
	v_lshl_or_b32 v10, s48, 6, v176
	v_mov_b32_e32 v11, v177
	v_lshlrev_b64 v[10:11], 2, v[10:11]
	v_lshl_add_u64 v[12:13], s[76:77], 0, v[10:11]
	v_lshl_add_u64 v[10:11], s[78:79], 0, v[10:11]
	global_load_dwordx4 v[66:69], v[12:13], off offset:16 nt
	global_load_dwordx4 v[70:73], v[12:13], off nt
	global_load_dwordx4 v[14:17], v[10:11], off offset:16 nt
	s_nop 0
	global_load_dwordx4 v[10:13], v[10:11], off nt
	s_waitcnt vmcnt(6)
	v_mov_b32_e32 v122, v134
	v_mov_b32_e32 v123, v135
	v_mov_b32_e32 v124, v136
	v_mov_b32_e32 v125, v137
	s_waitcnt vmcnt(5)
	v_mov_b32_e32 v118, v130
	v_mov_b32_e32 v119, v131
	v_mov_b32_e32 v120, v132
	v_mov_b32_e32 v121, v133
	s_waitcnt vmcnt(4)
	v_mov_b32_e32 v114, v126
	v_mov_b32_e32 v115, v127
	v_mov_b32_e32 v116, v128
	v_mov_b32_e32 v117, v129
.LBB0_515:
	s_or_b32 s46, s8, 3
	s_and_b64 vcc, exec, s[4:5]
	s_mov_b64 s[56:57], -1
	s_cbranch_vccnz .LBB0_519
	v_mov_b32_e32 v129, 0
	v_mov_b32_e32 v128, 0
	v_mov_b32_e32 v127, 0
	v_mov_b32_e32 v126, 0
	v_mov_b32_e32 v133, 0
	v_mov_b32_e32 v132, 0
	v_mov_b32_e32 v131, 0
	v_mov_b32_e32 v130, 0
	v_mov_b32_e32 v137, 0
	v_mov_b32_e32 v136, 0
	v_mov_b32_e32 v135, 0
	v_mov_b32_e32 v134, 0
	s_and_saveexec_b64 s[56:57], s[42:43]
	s_cbranch_execz .LBB0_518
	s_lshl_b32 s18, s46, 7
	s_mov_b32 s19, s9
	v_lshl_add_u64 v[126:127], v[174:175], 0, s[18:19]
	global_load_dwordx4 v[134:137], v[126:127], off nt
	global_load_dwordx4 v[130:133], v[126:127], off offset:1024 nt
	s_nop 0
	global_load_dwordx4 v[126:129], v[126:127], off offset:2048 nt

; __device__ __forceinline__ void bprep_item(const Params& P, LAS unsigned char* lds, int item, int tid, int lane, int wave) {
;     ...
;         for (int hi = 0; hi < 4; ++hi) { const int h = hb4 + hi;
;             if (mode != 2) { wq_[hi] = wk_[hi] = wv_[hi] = (v4u){0u, 0u, 0u, 0u};
;                 if (valid) { const bf16* rp = QKVB + (size_t)m * 1536 + h * 64 + 8 * part; wq_[hi] = *(const v4u*)rp; wk_[hi] = *(const v4u*)(rp + 512); wv_[hi] = *(const v4u*)(rp + 1024); } }
;             else { const size_t co = (((size_t)s * 512 + 64 * pi + tl) * 8 + h) * 64 + 8 * part;
;                 ck_[hi][0] = ((const f32x4*)(P.cache_k + co))[0]; ck_[hi][1] = ((const f32x4*)(P.cache_k + co))[1]; cv_[hi][0] = ((const f32x4*)(P.cache_v + co))[0]; cv_[hi][1] = ((const f32x4*)(P.cache_v + co))[1]; } }
.LBB0_520:
	v_lshl_or_b32 v2, s46, 6, v176
	v_mov_b32_e32 v3, v177
	v_lshlrev_b64 v[2:3], 2, v[2:3]
	v_lshl_add_u64 v[4:5], s[76:77], 0, v[2:3]
	v_lshl_add_u64 v[2:3], s[78:79], 0, v[2:3]
	global_load_dwordx4 v[58:61], v[4:5], off offset:16 nt
	global_load_dwordx4 v[62:65], v[4:5], off nt
	global_load_dwordx4 v[6:9], v[2:3], off offset:16 nt
	s_nop 0
	global_load_dwordx4 v[2:5], v[2:3], off nt
	s_waitcnt vmcnt(6)
	v_mov_b32_e32 v134, v34
	v_mov_b32_e32 v135, v35
	v_mov_b32_e32 v136, v36
	v_mov_b32_e32 v137, v37
	s_waitcnt vmcnt(5)
	v_mov_b32_e32 v130, v38
	v_mov_b32_e32 v131, v39
	v_mov_b32_e32 v132, v40
	v_mov_b32_e32 v133, v41
	s_waitcnt vmcnt(4)
	v_mov_b32_e32 v126, v186
	v_mov_b32_e32 v127, v187
	v_mov_b32_e32 v128, v188
	v_mov_b32_e32 v129, v189
